# mixer D: merged fast path for fully visible steps, both QK^T products issued up front so one sub-step's softmax overlaps the other's MFMAs
# speedup vs baseline: 1.1667x; 1.0111x over previous
; DI float fexp2(float x) { return __builtin_amdgcn_exp2f(x); }
; DI f32x16 mfma32(bf16x8 a, bf16x8 b, f32x16 c) { return __builtin_amdgcn_mfma_f32_32x32x16_bf16(a, b, c, 0, 0, 0); }
; DI float half_max(float v) { auto rr = __builtin_amdgcn_permlane32_swap(__float_as_uint(v), __float_as_uint(v), false, false); return fmaxf(__uint_as_float(rr[0]), __uint_as_float(rr[1])); }
; template <int DVB, bool MASKED = true>
; DI void attn_step32(const bf16* Kt, int KP, const bf16* Vt, int VP, const bf16x8 (&qf)[4], f32x16 (&o)[DVB], float& m, float& l, unsigned vmask, float c2, int lane) {
;   const int r32 = lane & 31, h = lane >> 5;
;   f32x16 s;
; #pragma unroll
;   for (int i = 0; i < 16; ++i) s[i] = 0.f;
; #pragma unroll
;   for (int t = 0; t < 4; ++t) { const bf16x8 kf = *(const bf16x8*)(Kt + r32 * KP + t * 16 + h * 8); s = mfma32(kf, qf[t], s); }
;   float mx = -INFINITY;
; #pragma unroll
;   for (int i = 0; i < 16; ++i) { if (MASKED) { s[i] = ((vmask >> i) & 1u) ? s[i] : -INFINITY; } mx = fmaxf(mx, s[i]); }
;   mx = half_max(mx);
;   const float mxs = mx * c2;
;   if (__any(mxs > m + 6.f)) {
;     const float mn = fmaxf(m, mxs);
;     const float alpha = fexp2(m - mn); l *= alpha;
; #pragma unroll
;     for (int d = 0; d < DVB; ++d)
; #pragma unroll
;       for (int i = 0; i < 16; ++i) o[d][i] *= alpha;
;     m = mn;
;   }
; DI void mixerD_unit(const Params& p, int b, int head, int qb, char* lds) {
;     ...
;     const bf16* Ks = map ? K2s : K1s;
; #pragma unroll
;     for (int sub = 0; sub < 2; ++sub) {
;       const int k0 = j * 64 + sub * 32;
;       if (k0 <= 128 * qb + 32 * qsub + 31) {
;         if (k0 + 31 <= 128 * qb + 32 * qsub) {
;           attn_step32<4, false>(Ks + sub * 32 * DKP, DKP, Vs + sub * 32 * DVP, DVP, qf, o, m, l, 0xffffu, 0.125f * LOG2E, lane);
.Ld_fast:
	ds_read_b128 v[66:69], v155
	ds_read_b128 v[156:159], v155 offset:32
	ds_read_b128 v[200:203], v155 offset:64
	ds_read_b128 v[164:167], v155 offset:96
	ds_read_b128 v[220:223], v155 offset:4608
	ds_read_b128 v[224:227], v155 offset:4640
	ds_read_b128 v[228:231], v155 offset:4672
	ds_read_b128 v[232:235], v155 offset:4704
	v_lshlrev_b32_e32 v216, 1, v133
	v_lshlrev_b32_e32 v217, 1, v147
	v_add3_u32 v218, v153, v216, v217
	s_waitcnt lgkmcnt(7)
	v_mfma_f32_32x32x16_bf16 v[66:81], v[66:69], v[90:93], 0
	s_waitcnt lgkmcnt(6)
	v_mfma_f32_32x32x16_bf16 v[66:81], v[156:159], v[82:85], v[66:81]
	s_waitcnt lgkmcnt(5)
	v_mfma_f32_32x32x16_bf16 v[66:81], v[200:203], v[86:89], v[66:81]
	s_waitcnt lgkmcnt(4)
	v_mfma_f32_32x32x16_bf16 v[66:81], v[164:167], v[94:97], v[66:81]
	s_waitcnt lgkmcnt(3)
	v_mfma_f32_32x32x16_bf16 v[236:251], v[220:223], v[90:93], 0
	s_waitcnt lgkmcnt(2)
	v_mfma_f32_32x32x16_bf16 v[236:251], v[224:227], v[82:85], v[236:251]
	s_waitcnt lgkmcnt(1)
	v_mfma_f32_32x32x16_bf16 v[236:251], v[228:231], v[86:89], v[236:251]
	s_waitcnt lgkmcnt(0)
	v_mfma_f32_32x32x16_bf16 v[236:251], v[232:235], v[94:97], v[236:251]
	ds_read_b64_tr_b16 v[204:205], v218 offset:18432
	ds_read_b64_tr_b16 v[206:207], v218 offset:20608
	ds_read_b64_tr_b16 v[208:209], v218 offset:22784
	ds_read_b64_tr_b16 v[210:211], v218 offset:24960
	ds_read_b64_tr_b16 v[156:157], v218 offset:18496
	ds_read_b64_tr_b16 v[160:161], v218 offset:18560
	ds_read_b64_tr_b16 v[164:165], v218 offset:18624
	ds_read_b64_tr_b16 v[158:159], v218 offset:20672
	ds_read_b64_tr_b16 v[162:163], v218 offset:20736
	ds_read_b64_tr_b16 v[166:167], v218 offset:20800
	ds_read_b64_tr_b16 v[212:213], v218 offset:22848
	ds_read_b64_tr_b16 v[168:169], v218 offset:22912
	ds_read_b64_tr_b16 v[172:173], v218 offset:22976
	ds_read_b64_tr_b16 v[214:215], v218 offset:25024
	ds_read_b64_tr_b16 v[170:171], v218 offset:25088
	ds_read_b64_tr_b16 v[174:175], v218 offset:25152
	v_add_f32_e32 v195, 0x40c00000, v154
	v_max3_f32 v216, v66, v67, v68
	v_max3_f32 v217, v69, v70, v71
	v_max3_f32 v219, v72, v73, v74
	v_max3_f32 v253, v75, v76, v77
	v_max3_f32 v194, v78, v79, v80
	v_max3_f32 v216, v216, v217, v219
	v_max3_f32 v253, v253, v194, v81
	v_max3_f32 v216, v216, v253, s56
	v_mov_b32_e32 v217, v216
	s_nop 1
	v_permlane32_swap_b32_e32 v216, v217
	v_max_f32_e32 v216, v216, v217
	v_mul_f32_e32 v216, 0x3e38aa3b, v216
	v_cmp_gt_f32_e32 vcc, v216, v195
	s_cbranch_vccz .Ld_fast_nr_a
	v_max_f32_e32 v196, v154, v216
	v_sub_f32_e32 v154, v154, v196
	v_exp_f32_e32 v154, v154
	s_nop 0
	v_mul_f32_e32 v64, v64, v154
	v_pk_mul_f32 v[62:63], v[62:63], v[154:155] op_sel_hi:[1,0]
	v_pk_mul_f32 v[60:61], v[60:61], v[154:155] op_sel_hi:[1,0]
	v_pk_mul_f32 v[58:59], v[58:59], v[154:155] op_sel_hi:[1,0]
	v_pk_mul_f32 v[56:57], v[56:57], v[154:155] op_sel_hi:[1,0]
	v_pk_mul_f32 v[54:55], v[54:55], v[154:155] op_sel_hi:[1,0]
	v_pk_mul_f32 v[52:53], v[52:53], v[154:155] op_sel_hi:[1,0]
	v_pk_mul_f32 v[50:51], v[50:51], v[154:155] op_sel_hi:[1,0]
	v_pk_mul_f32 v[48:49], v[48:49], v[154:155] op_sel_hi:[1,0]
	v_pk_mul_f32 v[46:47], v[46:47], v[154:155] op_sel_hi:[1,0]
	v_pk_mul_f32 v[44:45], v[44:45], v[154:155] op_sel_hi:[1,0]
	v_pk_mul_f32 v[42:43], v[42:43], v[154:155] op_sel_hi:[1,0]
	v_pk_mul_f32 v[40:41], v[40:41], v[154:155] op_sel_hi:[1,0]
	v_pk_mul_f32 v[38:39], v[38:39], v[154:155] op_sel_hi:[1,0]
	v_pk_mul_f32 v[36:37], v[36:37], v[154:155] op_sel_hi:[1,0]
	v_pk_mul_f32 v[34:35], v[34:35], v[154:155] op_sel_hi:[1,0]
	v_pk_mul_f32 v[32:33], v[32:33], v[154:155] op_sel_hi:[1,0]
	v_pk_mul_f32 v[30:31], v[30:31], v[154:155] op_sel_hi:[1,0]
	v_pk_mul_f32 v[28:29], v[28:29], v[154:155] op_sel_hi:[1,0]
	v_pk_mul_f32 v[26:27], v[26:27], v[154:155] op_sel_hi:[1,0]
	v_pk_mul_f32 v[24:25], v[24:25], v[154:155] op_sel_hi:[1,0]
	v_pk_mul_f32 v[22:23], v[22:23], v[154:155] op_sel_hi:[1,0]
	v_pk_mul_f32 v[20:21], v[20:21], v[154:155] op_sel_hi:[1,0]
	v_pk_mul_f32 v[18:19], v[18:19], v[154:155] op_sel_hi:[1,0]
	v_pk_mul_f32 v[16:17], v[16:17], v[154:155] op_sel_hi:[1,0]
	v_pk_mul_f32 v[14:15], v[14:15], v[154:155] op_sel_hi:[1,0]
	v_pk_mul_f32 v[12:13], v[12:13], v[154:155] op_sel_hi:[1,0]
	v_pk_mul_f32 v[10:11], v[10:11], v[154:155] op_sel_hi:[1,0]
	v_pk_mul_f32 v[8:9], v[8:9], v[154:155] op_sel_hi:[1,0]
	v_pk_mul_f32 v[6:7], v[6:7], v[154:155] op_sel_hi:[1,0]
	v_pk_mul_f32 v[4:5], v[4:5], v[154:155] op_sel_hi:[1,0]
	v_pk_mul_f32 v[2:3], v[2:3], v[154:155] op_sel_hi:[1,0]
	v_pk_mul_f32 v[0:1], v[0:1], v[154:155] op_sel_hi:[1,0]
	v_mov_b32_e32 v154, v196
; DI unsigned cvtpk(float lo, float hi) { f32x2_t v = {lo, hi}; bf16x2_t b = __builtin_convertvector(v, bf16x2_t); return __builtin_bit_cast(unsigned, b); }
; DI float fexp2(float x) { return __builtin_amdgcn_exp2f(x); }
; DI f32x16 mfma32(bf16x8 a, bf16x8 b, f32x16 c) { return __builtin_amdgcn_mfma_f32_32x32x16_bf16(a, b, c, 0, 0, 0); }
; DI s16x4 trread(const bf16* p) { return __builtin_bit_cast(s16x4, __builtin_amdgcn_ds_read_tr16_b64_v4i16((LAS s16x4*)p)); }
; DI float half_max(float v) { auto rr = __builtin_amdgcn_permlane32_swap(__float_as_uint(v), __float_as_uint(v), false, false); return fmaxf(__uint_as_float(rr[0]), __uint_as_float(rr[1])); }
; template <int DVB, bool MASKED = true>
; DI void attn_step32(const bf16* Kt, int KP, const bf16* Vt, int VP, const bf16x8 (&qf)[4], f32x16 (&o)[DVB], float& m, float& l, unsigned vmask, float c2, int lane) {
;     ...
;   float mx = -INFINITY;
; #pragma unroll
;   for (int i = 0; i < 16; ++i) { if (MASKED) { s[i] = ((vmask >> i) & 1u) ? s[i] : -INFINITY; } mx = fmaxf(mx, s[i]); }
;   mx = half_max(mx);
;   const float mxs = mx * c2;
;   if (__any(mxs > m + 6.f)) {
;     const float mn = fmaxf(m, mxs);
;     const float alpha = fexp2(m - mn); l *= alpha;
; #pragma unroll
;     for (int d = 0; d < DVB; ++d)
; #pragma unroll
;       for (int i = 0; i < 16; ++i) o[d][i] *= alpha;
;     m = mn;
;   }
;   float ps = 0.f; const float negm = -m;
; #pragma unroll
;   for (int i = 0; i < 16; ++i) { const float pv = fexp2(__builtin_fmaf(s[i], c2, negm)); s[i] = pv; ps += pv; }
;   l += ps;
;   bf16x8 pf[2];
;   { u32x4 a, b; a.x = cvtpk(s[0], s[1]); a.y = cvtpk(s[2], s[3]); a.z = cvtpk(s[4], s[5]); a.w = cvtpk(s[6], s[7]);
;     b.x = cvtpk(s[8], s[9]); b.y = cvtpk(s[10], s[11]); b.z = cvtpk(s[12], s[13]); b.w = cvtpk(s[14], s[15]);
;     pf[0] = __builtin_bit_cast(bf16x8, a); pf[1] = __builtin_bit_cast(bf16x8, b); }
;   const int i16 = lane & 15, q = i16 >> 2, pp = i16 & 3, blk = (lane >> 4) & 1;
; #pragma unroll
;   for (int d = 0; d < DVB; ++d)
; #pragma unroll
;     for (int sk = 0; sk < 2; ++sk) {
;       const s16x4 lo = trread(Vt + (16 * sk + 4 * h + q) * VP + 32 * d + 16 * blk + 4 * pp);
;       const s16x4 hi = trread(Vt + (16 * sk + 8 + 4 * h + q) * VP + 32 * d + 16 * blk + 4 * pp);
;       const bf16x8 vf = __builtin_shufflevector(lo, hi, 0, 1, 2, 3, 4, 5, 6, 7);
;       o[d] = mfma32(vf, pf[sk], o[d]);
;     }
.Ld_fast_nr_a:
	v_fma_f32 v66, v66, s57, -v154
	v_fma_f32 v67, v67, s57, -v154
	v_fma_f32 v68, v68, s57, -v154
	v_fma_f32 v69, v69, s57, -v154
	v_fma_f32 v70, v70, s57, -v154
	v_fma_f32 v71, v71, s57, -v154
	v_fma_f32 v72, v72, s57, -v154
	v_fma_f32 v73, v73, s57, -v154
	v_fma_f32 v74, v74, s57, -v154
	v_fma_f32 v75, v75, s57, -v154
	v_fma_f32 v76, v76, s57, -v154
	v_fma_f32 v77, v77, s57, -v154
	v_fma_f32 v78, v78, s57, -v154
	v_fma_f32 v79, v79, s57, -v154
	v_fma_f32 v80, v80, s57, -v154
	v_fma_f32 v81, v81, s57, -v154
	v_exp_f32_e32 v176, v66
	v_exp_f32_e32 v177, v67
	v_exp_f32_e32 v178, v68
	v_exp_f32_e32 v179, v69
	v_exp_f32_e32 v180, v70
	v_exp_f32_e32 v181, v71
	v_exp_f32_e32 v184, v72
	v_exp_f32_e32 v185, v73
	v_exp_f32_e32 v186, v74
	v_exp_f32_e32 v187, v75
	v_exp_f32_e32 v188, v76
	v_exp_f32_e32 v189, v77
	v_exp_f32_e32 v190, v78
	v_exp_f32_e32 v191, v79
	v_exp_f32_e32 v192, v80
	v_exp_f32_e32 v193, v81
	v_cvt_pk_bf16_f32 v66, v176, v177
	v_cvt_pk_bf16_f32 v67, v178, v179
	v_cvt_pk_bf16_f32 v68, v180, v181
	v_cvt_pk_bf16_f32 v69, v184, v185
	v_cvt_pk_bf16_f32 v70, v186, v187
	v_cvt_pk_bf16_f32 v71, v188, v189
	v_cvt_pk_bf16_f32 v72, v190, v191
	v_cvt_pk_bf16_f32 v73, v192, v193
	v_add_f32_e32 v74, v176, v177
	v_add_f32_e32 v75, v186, v187
	s_waitcnt lgkmcnt(0)
	v_mfma_f32_32x32x16_bf16 v[32:47], v[156:159], v[66:69], v[32:47]
	v_add_f32_e32 v74, v178, v74
	v_add_f32_e32 v75, v188, v75
	v_mfma_f32_32x32x16_bf16 v[48:63], v[204:207], v[66:69], v[48:63]
	v_add_f32_e32 v74, v179, v74
	v_add_f32_e32 v75, v189, v75
	v_mfma_f32_32x32x16_bf16 v[32:47], v[212:215], v[70:73], v[32:47]
	v_add_f32_e32 v74, v180, v74
	v_add_f32_e32 v75, v190, v75
	v_mfma_f32_32x32x16_bf16 v[16:31], v[160:163], v[66:69], v[16:31]
	v_add_f32_e32 v74, v181, v74
	v_add_f32_e32 v75, v191, v75
	v_mfma_f32_32x32x16_bf16 v[0:15], v[164:167], v[66:69], v[0:15]
	v_add_f32_e32 v74, v184, v74
	v_add_f32_e32 v75, v192, v75
	v_mfma_f32_32x32x16_bf16 v[48:63], v[208:211], v[70:73], v[48:63]
	v_add_f32_e32 v74, v185, v74
	v_add_f32_e32 v75, v193, v75
	v_mfma_f32_32x32x16_bf16 v[16:31], v[168:171], v[70:73], v[16:31]
	v_add_f32_e32 v74, v74, v75
	v_add_f32_e32 v64, v64, v74
	v_mfma_f32_32x32x16_bf16 v[0:15], v[172:175], v[70:73], v[0:15]
	ds_read_b64_tr_b16 v[204:205], v218 offset:27136
	ds_read_b64_tr_b16 v[206:207], v218 offset:29312
	ds_read_b64_tr_b16 v[208:209], v218 offset:31488
	ds_read_b64_tr_b16 v[210:211], v218 offset:33664
	ds_read_b64_tr_b16 v[156:157], v218 offset:27200
	ds_read_b64_tr_b16 v[160:161], v218 offset:27264
	ds_read_b64_tr_b16 v[164:165], v218 offset:27328
	ds_read_b64_tr_b16 v[158:159], v218 offset:29376
	ds_read_b64_tr_b16 v[162:163], v218 offset:29440
	ds_read_b64_tr_b16 v[166:167], v218 offset:29504
	ds_read_b64_tr_b16 v[212:213], v218 offset:31552
	ds_read_b64_tr_b16 v[168:169], v218 offset:31616
	ds_read_b64_tr_b16 v[172:173], v218 offset:31680
	ds_read_b64_tr_b16 v[214:215], v218 offset:33728
	ds_read_b64_tr_b16 v[170:171], v218 offset:33792
	ds_read_b64_tr_b16 v[174:175], v218 offset:33856
	v_add_f32_e32 v195, 0x40c00000, v154
	v_max3_f32 v216, v236, v237, v238
	v_max3_f32 v217, v239, v240, v241
	v_max3_f32 v219, v242, v243, v244
	v_max3_f32 v253, v245, v246, v247
	v_max3_f32 v194, v248, v249, v250
	v_max3_f32 v216, v216, v217, v219
	v_max3_f32 v253, v253, v194, v251
	v_max3_f32 v216, v216, v253, s56
	v_mov_b32_e32 v217, v216
	s_nop 1
	v_permlane32_swap_b32_e32 v216, v217
	v_max_f32_e32 v216, v216, v217
	v_mul_f32_e32 v216, 0x3e38aa3b, v216
	v_cmp_gt_f32_e32 vcc, v216, v195
	s_cbranch_vccz .Ld_fast_nr_b
	v_max_f32_e32 v196, v154, v216
	v_sub_f32_e32 v154, v154, v196
	v_exp_f32_e32 v154, v154
	s_nop 0
	v_mul_f32_e32 v64, v64, v154
	v_pk_mul_f32 v[62:63], v[62:63], v[154:155] op_sel_hi:[1,0]
	v_pk_mul_f32 v[60:61], v[60:61], v[154:155] op_sel_hi:[1,0]
	v_pk_mul_f32 v[58:59], v[58:59], v[154:155] op_sel_hi:[1,0]
	v_pk_mul_f32 v[56:57], v[56:57], v[154:155] op_sel_hi:[1,0]
	v_pk_mul_f32 v[54:55], v[54:55], v[154:155] op_sel_hi:[1,0]
	v_pk_mul_f32 v[52:53], v[52:53], v[154:155] op_sel_hi:[1,0]
	v_pk_mul_f32 v[50:51], v[50:51], v[154:155] op_sel_hi:[1,0]
	v_pk_mul_f32 v[48:49], v[48:49], v[154:155] op_sel_hi:[1,0]
	v_pk_mul_f32 v[46:47], v[46:47], v[154:155] op_sel_hi:[1,0]
	v_pk_mul_f32 v[44:45], v[44:45], v[154:155] op_sel_hi:[1,0]
	v_pk_mul_f32 v[42:43], v[42:43], v[154:155] op_sel_hi:[1,0]
	v_pk_mul_f32 v[40:41], v[40:41], v[154:155] op_sel_hi:[1,0]
	v_pk_mul_f32 v[38:39], v[38:39], v[154:155] op_sel_hi:[1,0]
	v_pk_mul_f32 v[36:37], v[36:37], v[154:155] op_sel_hi:[1,0]
	v_pk_mul_f32 v[34:35], v[34:35], v[154:155] op_sel_hi:[1,0]
	v_pk_mul_f32 v[32:33], v[32:33], v[154:155] op_sel_hi:[1,0]
	v_pk_mul_f32 v[30:31], v[30:31], v[154:155] op_sel_hi:[1,0]
	v_pk_mul_f32 v[28:29], v[28:29], v[154:155] op_sel_hi:[1,0]
	v_pk_mul_f32 v[26:27], v[26:27], v[154:155] op_sel_hi:[1,0]
	v_pk_mul_f32 v[24:25], v[24:25], v[154:155] op_sel_hi:[1,0]
	v_pk_mul_f32 v[22:23], v[22:23], v[154:155] op_sel_hi:[1,0]
	v_pk_mul_f32 v[20:21], v[20:21], v[154:155] op_sel_hi:[1,0]
	v_pk_mul_f32 v[18:19], v[18:19], v[154:155] op_sel_hi:[1,0]
	v_pk_mul_f32 v[16:17], v[16:17], v[154:155] op_sel_hi:[1,0]
	v_pk_mul_f32 v[14:15], v[14:15], v[154:155] op_sel_hi:[1,0]
	v_pk_mul_f32 v[12:13], v[12:13], v[154:155] op_sel_hi:[1,0]
	v_pk_mul_f32 v[10:11], v[10:11], v[154:155] op_sel_hi:[1,0]
	v_pk_mul_f32 v[8:9], v[8:9], v[154:155] op_sel_hi:[1,0]
	v_pk_mul_f32 v[6:7], v[6:7], v[154:155] op_sel_hi:[1,0]
	v_pk_mul_f32 v[4:5], v[4:5], v[154:155] op_sel_hi:[1,0]
	v_pk_mul_f32 v[2:3], v[2:3], v[154:155] op_sel_hi:[1,0]
	v_pk_mul_f32 v[0:1], v[0:1], v[154:155] op_sel_hi:[1,0]
	v_mov_b32_e32 v154, v196
; DI unsigned cvtpk(float lo, float hi) { f32x2_t v = {lo, hi}; bf16x2_t b = __builtin_convertvector(v, bf16x2_t); return __builtin_bit_cast(unsigned, b); }
; DI float fexp2(float x) { return __builtin_amdgcn_exp2f(x); }
; DI f32x16 mfma32(bf16x8 a, bf16x8 b, f32x16 c) { return __builtin_amdgcn_mfma_f32_32x32x16_bf16(a, b, c, 0, 0, 0); }
; DI s16x4 trread(const bf16* p) { return __builtin_bit_cast(s16x4, __builtin_amdgcn_ds_read_tr16_b64_v4i16((LAS s16x4*)p)); }
; template <int DVB, bool MASKED = true>
; DI void attn_step32(const bf16* Kt, int KP, const bf16* Vt, int VP, const bf16x8 (&qf)[4], f32x16 (&o)[DVB], float& m, float& l, unsigned vmask, float c2, int lane) {
;     ...
;   float ps = 0.f; const float negm = -m;
; #pragma unroll
;   for (int i = 0; i < 16; ++i) { const float pv = fexp2(__builtin_fmaf(s[i], c2, negm)); s[i] = pv; ps += pv; }
;   l += ps;
;   bf16x8 pf[2];
;   { u32x4 a, b; a.x = cvtpk(s[0], s[1]); a.y = cvtpk(s[2], s[3]); a.z = cvtpk(s[4], s[5]); a.w = cvtpk(s[6], s[7]);
;     b.x = cvtpk(s[8], s[9]); b.y = cvtpk(s[10], s[11]); b.z = cvtpk(s[12], s[13]); b.w = cvtpk(s[14], s[15]);
;     pf[0] = __builtin_bit_cast(bf16x8, a); pf[1] = __builtin_bit_cast(bf16x8, b); }
;   const int i16 = lane & 15, q = i16 >> 2, pp = i16 & 3, blk = (lane >> 4) & 1;
; #pragma unroll
;   for (int d = 0; d < DVB; ++d)
; #pragma unroll
;     for (int sk = 0; sk < 2; ++sk) {
;       const s16x4 lo = trread(Vt + (16 * sk + 4 * h + q) * VP + 32 * d + 16 * blk + 4 * pp);
;       const s16x4 hi = trread(Vt + (16 * sk + 8 + 4 * h + q) * VP + 32 * d + 16 * blk + 4 * pp);
;       const bf16x8 vf = __builtin_shufflevector(lo, hi, 0, 1, 2, 3, 4, 5, 6, 7);
;       o[d] = mfma32(vf, pf[sk], o[d]);
;     }
.Ld_fast_nr_b:
	v_fma_f32 v236, v236, s57, -v154
	v_fma_f32 v237, v237, s57, -v154
	v_fma_f32 v238, v238, s57, -v154
	v_fma_f32 v239, v239, s57, -v154
	v_fma_f32 v240, v240, s57, -v154
	v_fma_f32 v241, v241, s57, -v154
	v_fma_f32 v242, v242, s57, -v154
	v_fma_f32 v243, v243, s57, -v154
	v_fma_f32 v244, v244, s57, -v154
	v_fma_f32 v245, v245, s57, -v154
	v_fma_f32 v246, v246, s57, -v154
	v_fma_f32 v247, v247, s57, -v154
	v_fma_f32 v248, v248, s57, -v154
	v_fma_f32 v249, v249, s57, -v154
	v_fma_f32 v250, v250, s57, -v154
	v_fma_f32 v251, v251, s57, -v154
	v_exp_f32_e32 v176, v236
	v_exp_f32_e32 v177, v237
	v_exp_f32_e32 v178, v238
	v_exp_f32_e32 v179, v239
	v_exp_f32_e32 v180, v240
	v_exp_f32_e32 v181, v241
	v_exp_f32_e32 v184, v242
	v_exp_f32_e32 v185, v243
	v_exp_f32_e32 v186, v244
	v_exp_f32_e32 v187, v245
	v_exp_f32_e32 v188, v246
	v_exp_f32_e32 v189, v247
	v_exp_f32_e32 v190, v248
	v_exp_f32_e32 v191, v249
	v_exp_f32_e32 v192, v250
	v_exp_f32_e32 v193, v251
	v_cvt_pk_bf16_f32 v66, v176, v177
	v_cvt_pk_bf16_f32 v67, v178, v179
	v_cvt_pk_bf16_f32 v68, v180, v181
	v_cvt_pk_bf16_f32 v69, v184, v185
	v_cvt_pk_bf16_f32 v70, v186, v187
	v_cvt_pk_bf16_f32 v71, v188, v189
	v_cvt_pk_bf16_f32 v72, v190, v191
	v_cvt_pk_bf16_f32 v73, v192, v193
	v_add_f32_e32 v74, v176, v177
	v_add_f32_e32 v75, v186, v187
	s_waitcnt lgkmcnt(0)
	v_mfma_f32_32x32x16_bf16 v[32:47], v[156:159], v[66:69], v[32:47]
	v_add_f32_e32 v74, v178, v74
	v_add_f32_e32 v75, v188, v75
	v_mfma_f32_32x32x16_bf16 v[48:63], v[204:207], v[66:69], v[48:63]
	v_add_f32_e32 v74, v179, v74
	v_add_f32_e32 v75, v189, v75
	v_mfma_f32_32x32x16_bf16 v[32:47], v[212:215], v[70:73], v[32:47]
	v_add_f32_e32 v74, v180, v74
	v_add_f32_e32 v75, v190, v75
	v_mfma_f32_32x32x16_bf16 v[16:31], v[160:163], v[66:69], v[16:31]
	v_add_f32_e32 v74, v181, v74
	v_add_f32_e32 v75, v191, v75
	v_mfma_f32_32x32x16_bf16 v[0:15], v[164:167], v[66:69], v[0:15]
	v_add_f32_e32 v74, v184, v74
	v_add_f32_e32 v75, v192, v75
	v_mfma_f32_32x32x16_bf16 v[48:63], v[208:211], v[70:73], v[48:63]
	v_add_f32_e32 v74, v185, v74
	v_add_f32_e32 v75, v193, v75
	v_mfma_f32_32x32x16_bf16 v[16:31], v[168:171], v[70:73], v[16:31]
	v_add_f32_e32 v74, v74, v75
	v_add_f32_e32 v64, v64, v74
	v_mfma_f32_32x32x16_bf16 v[0:15], v[172:175], v[70:73], v[0:15]
	s_branch .Ld_fast_done

; #define D_LOAD(j) do { const int row = tid >> 3, ch = tid & 7; const size_t off = (size_t)((j) * 64 + row) * NPO + ch * 8; rk1 = *(const u32x4*)(K1g + off); rk2 = *(const u32x4*)(K2g + off); \
;     _Pragma("unroll") for (int i = 0; i < 2; ++i) { const int c = tid + 512 * i, vr = c >> 4, vc = c & 15; rv[i] = *(const u32x4*)(Vg + (size_t)((j) * 64 + vr) * NPO + vc * 8); } } while (0)
; DI void mixerD_unit(const Params& p, int b, int head, int qb, char* lds) {
;     ...
;   for (int j = 0; j < nsteps; ++j) {
;     char* st = lds + (j & 1) * D_STAGE;
;     bf16* K1s = (bf16*)st; bf16* K2s = K1s + 64 * DKP; bf16* Vs = K2s + 64 * DKP;
;     { const int row = tid >> 3, ch = tid & 7; *(u32x4*)(K1s + row * DKP + ch * 8) = rk1; *(u32x4*)(K2s + row * DKP + ch * 8) = rk2;
; #pragma unroll
;       for (int i = 0; i < 2; ++i) { const int c = tid + 512 * i, vr = c >> 4, vc = c & 15; *(u32x4*)(Vs + vr * DVP + vc * 8) = rv[i]; } }
;     __syncthreads();
;     if (j + 1 < nsteps) D_LOAD(j + 1);
;     const bf16* Ks = map ? K2s : K1s;
; #pragma unroll
;     for (int sub = 0; sub < 2; ++sub) {
;       const int k0 = j * 64 + sub * 32;
;       if (k0 <= 128 * qb + 32 * qsub + 31) {
;         if (k0 + 31 <= 128 * qb + 32 * qsub) {
;           attn_step32<4, false>(Ks + sub * 32 * DKP, DKP, Vs + sub * 32 * DVP, DVP, qf, o, m, l, 0xffffu, 0.125f * LOG2E, lane);
.Ld_fast_done:
	s_add_i32 s65, s65, 64
	s_cmp_eq_u32 s64, s63
	s_cbranch_scc1 .LBB0_2607

; DI float fexp2(float x) { return __builtin_amdgcn_exp2f(x); }
; DI f32x16 mfma32(bf16x8 a, bf16x8 b, f32x16 c) { return __builtin_amdgcn_mfma_f32_32x32x16_bf16(a, b, c, 0, 0, 0); }
; DI int crow(int i, int h) { return (i & 3) + 8 * (i >> 2) + 4 * h; }
; DI float half_max(float v) { auto rr = __builtin_amdgcn_permlane32_swap(__float_as_uint(v), __float_as_uint(v), false, false); return fmaxf(__uint_as_float(rr[0]), __uint_as_float(rr[1])); }
; template <int DVB, bool MASKED = true>
; DI void attn_step32(const bf16* Kt, int KP, const bf16* Vt, int VP, const bf16x8 (&qf)[4], f32x16 (&o)[DVB], float& m, float& l, unsigned vmask, float c2, int lane) {
;   const int r32 = lane & 31, h = lane >> 5;
;   f32x16 s;
; #pragma unroll
;   for (int i = 0; i < 16; ++i) s[i] = 0.f;
; #pragma unroll
;   for (int t = 0; t < 4; ++t) { const bf16x8 kf = *(const bf16x8*)(Kt + r32 * KP + t * 16 + h * 8); s = mfma32(kf, qf[t], s); }
;   float mx = -INFINITY;
; #pragma unroll
;   for (int i = 0; i < 16; ++i) { if (MASKED) { s[i] = ((vmask >> i) & 1u) ? s[i] : -INFINITY; } mx = fmaxf(mx, s[i]); }
;   mx = half_max(mx);
;   const float mxs = mx * c2;
;   if (__any(mxs > m + 6.f)) {
;     const float mn = fmaxf(m, mxs);
;     const float alpha = fexp2(m - mn); l *= alpha;
; #pragma unroll
;     for (int d = 0; d < DVB; ++d)
; #pragma unroll
;       for (int i = 0; i < 16; ++i) o[d][i] *= alpha;
;     m = mn;
;   }
; DI void mixerD_unit(const Params& p, int b, int head, int qb, char* lds) {
;     ...
;     const bf16* Ks = map ? K2s : K1s;
; #pragma unroll
;     for (int sub = 0; sub < 2; ++sub) {
;       const int k0 = j * 64 + sub * 32;
;       if (k0 <= 128 * qb + 32 * qsub + 31) {
;         if (k0 + 31 <= 128 * qb + 32 * qsub) {
;           attn_step32<4, false>(Ks + sub * 32 * DKP, DKP, Vs + sub * 32 * DVP, DVP, qf, o, m, l, 0xffffu, 0.125f * LOG2E, lane);
;         } else {
;           unsigned vm = 0;
; #pragma unroll
;           for (int i = 0; i < 16; ++i) if (k0 + crow(i, h) <= qpos) vm |= (1u << i);
;           attn_step32<4, true>(Ks + sub * 32 * DKP, DKP, Vs + sub * 32 * DVP, DVP, qf, o, m, l, vm, 0.125f * LOG2E, lane);
.LBB0_2588:
	s_add_i32 s1, s0, 0x2400
	v_mov_b32_e32 v66, s1
	v_mov_b32_e32 v67, s0
	v_cndmask_b32_e64 v66, v66, v67, s[6:7]
	s_sub_i32 s1, s65, 32
	v_add3_u32 v155, v66, v131, v152
	v_add_u32_e32 v153, s0, v148
	v_readfirstlane_b32 s8, v65
	s_add_i32 s9, s65, 31
	s_cmp_le_i32 s9, s8
	s_cbranch_scc1 .Ld_fast
	v_cmp_le_i32_e32 vcc, s1, v125
	s_and_saveexec_b64 s[0:1], vcc
	s_cbranch_execz .LBB0_2598
	s_add_i32 s2, s65, -1
	v_cmp_le_i32_e32 vcc, s2, v65
	v_add_f32_e32 v163, 0x40c00000, v154
	s_and_saveexec_b64 s[2:3], vcc
	s_xor_b64 s[2:3], exec, s[2:3]
	s_cbranch_execz .LBB0_2593
	ds_read_b128 v[66:69], v155
	ds_read_b128 v[156:159], v155 offset:32
	ds_read_b128 v[200:203], v155 offset:64
	ds_read_b128 v[164:167], v155 offset:96
	s_waitcnt lgkmcnt(3)
	v_mfma_f32_32x32x16_bf16 v[66:81], v[66:69], v[90:93], 0
	s_waitcnt lgkmcnt(2)
	v_mfma_f32_32x32x16_bf16 v[66:81], v[156:159], v[82:85], v[66:81]
	s_waitcnt lgkmcnt(1)
	v_mfma_f32_32x32x16_bf16 v[66:81], v[200:203], v[86:89], v[66:81]
	s_waitcnt lgkmcnt(0)
	v_mfma_f32_32x32x16_bf16 v[66:81], v[164:167], v[94:97], v[66:81]
	v_lshlrev_b32_e32 v216, 1, v133
	v_lshlrev_b32_e32 v217, 1, v147
	v_add3_u32 v218, v153, v216, v217
	v_add_f32_e32 v240, 0x40c00000, v154
	ds_read_b64_tr_b16 v[204:205], v218 offset:18432
	ds_read_b64_tr_b16 v[206:207], v218 offset:20608
	ds_read_b64_tr_b16 v[208:209], v218 offset:22784
	ds_read_b64_tr_b16 v[210:211], v218 offset:24960
	ds_read_b64_tr_b16 v[156:157], v218 offset:18496
	ds_read_b64_tr_b16 v[160:161], v218 offset:18560
	ds_read_b64_tr_b16 v[164:165], v218 offset:18624
	ds_read_b64_tr_b16 v[158:159], v218 offset:20672
	ds_read_b64_tr_b16 v[162:163], v218 offset:20736
	ds_read_b64_tr_b16 v[166:167], v218 offset:20800
	ds_read_b64_tr_b16 v[212:213], v218 offset:22848
	ds_read_b64_tr_b16 v[168:169], v218 offset:22912
	ds_read_b64_tr_b16 v[172:173], v218 offset:22976
	ds_read_b64_tr_b16 v[214:215], v218 offset:25024
	ds_read_b64_tr_b16 v[170:171], v218 offset:25088
	ds_read_b64_tr_b16 v[174:175], v218 offset:25152
	v_max3_f32 v219, v66, v67, v68
	v_max3_f32 v220, v69, v70, v71
	v_max3_f32 v221, v72, v73, v74
	v_max3_f32 v222, v75, v76, v77
	v_max3_f32 v223, v78, v79, v80
	v_max3_f32 v219, v219, v220, v221
	v_max3_f32 v222, v222, v223, v81
	v_max3_f32 v219, v219, v222, s56
	v_mov_b32_e32 v220, v219
	s_nop 1
	v_permlane32_swap_b32_e32 v219, v220
	v_max_f32_e32 v219, v219, v220
	v_mul_f32_e32 v219, 0x3e38aa3b, v219
	v_cmp_gt_f32_e32 vcc, v219, v240
	s_cbranch_vccz .Ld_norescale_u0
	v_max_f32_e32 v220, v154, v219
	v_sub_f32_e32 v154, v154, v220
	v_exp_f32_e32 v154, v154
	s_nop 0
	v_mul_f32_e32 v64, v64, v154
	v_pk_mul_f32 v[62:63], v[62:63], v[154:155] op_sel_hi:[1,0]
	v_pk_mul_f32 v[60:61], v[60:61], v[154:155] op_sel_hi:[1,0]
	v_pk_mul_f32 v[58:59], v[58:59], v[154:155] op_sel_hi:[1,0]
	v_pk_mul_f32 v[56:57], v[56:57], v[154:155] op_sel_hi:[1,0]
	v_pk_mul_f32 v[54:55], v[54:55], v[154:155] op_sel_hi:[1,0]
	v_pk_mul_f32 v[52:53], v[52:53], v[154:155] op_sel_hi:[1,0]
	v_pk_mul_f32 v[50:51], v[50:51], v[154:155] op_sel_hi:[1,0]
	v_pk_mul_f32 v[48:49], v[48:49], v[154:155] op_sel_hi:[1,0]
	v_pk_mul_f32 v[46:47], v[46:47], v[154:155] op_sel_hi:[1,0]
	v_pk_mul_f32 v[44:45], v[44:45], v[154:155] op_sel_hi:[1,0]
	v_pk_mul_f32 v[42:43], v[42:43], v[154:155] op_sel_hi:[1,0]
	v_pk_mul_f32 v[40:41], v[40:41], v[154:155] op_sel_hi:[1,0]
	v_pk_mul_f32 v[38:39], v[38:39], v[154:155] op_sel_hi:[1,0]
	v_pk_mul_f32 v[36:37], v[36:37], v[154:155] op_sel_hi:[1,0]
	v_pk_mul_f32 v[34:35], v[34:35], v[154:155] op_sel_hi:[1,0]
	v_pk_mul_f32 v[32:33], v[32:33], v[154:155] op_sel_hi:[1,0]
	v_pk_mul_f32 v[30:31], v[30:31], v[154:155] op_sel_hi:[1,0]
	v_pk_mul_f32 v[28:29], v[28:29], v[154:155] op_sel_hi:[1,0]
	v_pk_mul_f32 v[26:27], v[26:27], v[154:155] op_sel_hi:[1,0]
	v_pk_mul_f32 v[24:25], v[24:25], v[154:155] op_sel_hi:[1,0]
	v_pk_mul_f32 v[22:23], v[22:23], v[154:155] op_sel_hi:[1,0]
	v_pk_mul_f32 v[20:21], v[20:21], v[154:155] op_sel_hi:[1,0]
	v_pk_mul_f32 v[18:19], v[18:19], v[154:155] op_sel_hi:[1,0]
	v_pk_mul_f32 v[16:17], v[16:17], v[154:155] op_sel_hi:[1,0]
	v_pk_mul_f32 v[14:15], v[14:15], v[154:155] op_sel_hi:[1,0]
	v_pk_mul_f32 v[12:13], v[12:13], v[154:155] op_sel_hi:[1,0]
	v_pk_mul_f32 v[10:11], v[10:11], v[154:155] op_sel_hi:[1,0]
	v_pk_mul_f32 v[8:9], v[8:9], v[154:155] op_sel_hi:[1,0]
	v_pk_mul_f32 v[6:7], v[6:7], v[154:155] op_sel_hi:[1,0]
	v_pk_mul_f32 v[4:5], v[4:5], v[154:155] op_sel_hi:[1,0]
	v_pk_mul_f32 v[2:3], v[2:3], v[154:155] op_sel_hi:[1,0]
	v_pk_mul_f32 v[0:1], v[0:1], v[154:155] op_sel_hi:[1,0]
	v_mov_b32_e32 v154, v220
